# plus: lru_out carry-prefix loads batched (7 serial round trips -> 1), static s_setprio 1 for waves 4-7 in attention
# speedup vs baseline: 1.0057x; 1.0057x over previous
; __device__ __forceinline__ int ltid(int wv) { int l; asm volatile("v_mbcnt_lo_u32_b32 %0, -1, 0\n\tv_mbcnt_hi_u32_b32 %0, -1, %0" : "=v"(l)); asm volatile("" : "+s"(wv)); return (wv << 6) | l; }
; DI void lru_out(const Args& a, int unit, int wv) {
;     const int tid = ltid(wv), c = unit & (NCH - 1), b = unit >> 7, row0 = b * SEQ + c * 128, ch = (tid & 63) * 4, k = wv;
;     const u32x4* LAI = (const u32x4*)(a.ws + WS_LA); const bf16_t* Hg = (const bf16_t*)(a.ws + WS_H); bf16_t* Y = (bf16_t*)(a.ws + WS_Y);
;     const f32x4* LSWc = (const f32x4*)((const f32x2*)(a.ws + WS_LSW) + (size_t)(b * NCH + c) * 8 * 256);
;     f32x4 h = *(const f32x4*)((const float*)(a.ws + WS_LCARRY) + (size_t)(b * NCH + c) * 256 + ch);
;     f32x4 t0[7], t1[7];
; #pragma unroll
;     for (int w = 0; w < 7; ++w) if (w < k) { t0[w] = LSWc[(w * 256 + ch) / 2]; t1[w] = LSWc[(w * 256 + ch) / 2 + 1]; }
; #pragma unroll
;     for (int w = 0; w < 7; ++w) if (w < k) { h[0] = t0[w][0] * h[0] + t0[w][1]; h[1] = t0[w][2] * h[1] + t0[w][3]; h[2] = t1[w][0] * h[2] + t1[w][1]; h[3] = t1[w][2] * h[3] + t1[w][3]; }
; __global__ void __launch_bounds__(512, 2) hybrid_fwd(Args unused_args) {
;     ...
; for (int rep_ = 0; rep_ < REP_ATTN; ++rep_) {
;     ...
;         { PH_LOCALS
;           const attn_body::AttnTensors AT{(const attn_body::bf16*)((unsigned char*)a.out + DO_Q), (const attn_body::bf16*)((unsigned char*)a.out + DO_K), (const attn_body::bf16*)((unsigned char*)a.out + DO_V), (attn_body::bf16*)Yb};
;           const attn_body::StaticOrder S(G, bid);
;           attn_body::attn_phase<attn_body::StaticOrder>((char*)lds_raw, AT, S, wv0); }
.LBB0_1574:
	s_mov_b32 s2, s77
	v_mbcnt_lo_u32_b32 v64, -1, 0
	v_mbcnt_hi_u32_b32 v64, -1, v64
	s_add_u32 s2, s20, s7
	v_and_b32_e32 v0, 63, v64
	v_lshlrev_b32_e32 v2, 4, v0
	s_addc_u32 s3, s21, s12
	global_load_dwordx4 v[2:5], v2, s[2:3]
	v_lshlrev_b32_e32 v0, 5, v0
	s_add_u32 s2, s20, s24
	s_addc_u32 s3, s21, s25
	s_add_u32 s2, s2, 0x18800000
	s_addc_u32 s3, s3, 0
	global_load_dwordx4 v[108:111], v0, s[2:3]
	global_load_dwordx4 v[112:115], v0, s[2:3] offset:16
	s_add_u32 s2, s2, 0x800
	s_addc_u32 s3, s3, 0
	global_load_dwordx4 v[116:119], v0, s[2:3]
	global_load_dwordx4 v[120:123], v0, s[2:3] offset:16
	s_add_u32 s2, s2, 0x800
	s_addc_u32 s3, s3, 0
	global_load_dwordx4 v[124:127], v0, s[2:3]
	global_load_dwordx4 v[128:131], v0, s[2:3] offset:16
	s_add_u32 s2, s2, 0x800
	s_addc_u32 s3, s3, 0
	global_load_dwordx4 v[132:135], v0, s[2:3]
	global_load_dwordx4 v[136:139], v0, s[2:3] offset:16
	s_add_u32 s2, s2, 0x800
	s_addc_u32 s3, s3, 0
	global_load_dwordx4 v[140:143], v0, s[2:3]
	global_load_dwordx4 v[144:147], v0, s[2:3] offset:16
	s_add_u32 s2, s2, 0x800
	s_addc_u32 s3, s3, 0
	global_load_dwordx4 v[148:151], v0, s[2:3]
	global_load_dwordx4 v[152:155], v0, s[2:3] offset:16
	s_add_u32 s2, s2, 0x800
	s_addc_u32 s3, s3, 0
	global_load_dwordx4 v[156:159], v0, s[2:3]
	global_load_dwordx4 v[160:163], v0, s[2:3] offset:16
	s_waitcnt vmcnt(0)
	v_mov_b32_e32 v6, v112
	v_mov_b32_e32 v7, v114
	v_mov_b32_e32 v50, v113
	v_mov_b32_e32 v51, v115
	v_mov_b32_e32 v10, v108
	v_mov_b32_e32 v11, v110
	v_mov_b32_e32 v8, v109
	v_mov_b32_e32 v9, v111
	v_mov_b32_e32 v12, v120
	v_mov_b32_e32 v13, v122
	v_mov_b32_e32 v52, v121
	v_mov_b32_e32 v53, v123
	v_mov_b32_e32 v16, v116
	v_mov_b32_e32 v17, v118
	v_mov_b32_e32 v14, v117
	v_mov_b32_e32 v15, v119
	v_mov_b32_e32 v18, v128
	v_mov_b32_e32 v19, v130
	v_mov_b32_e32 v54, v129
	v_mov_b32_e32 v55, v131
	v_mov_b32_e32 v22, v124
	v_mov_b32_e32 v23, v126
	v_mov_b32_e32 v20, v125
	v_mov_b32_e32 v21, v127
	v_mov_b32_e32 v24, v136
	v_mov_b32_e32 v25, v138
	v_mov_b32_e32 v56, v137
	v_mov_b32_e32 v57, v139
	v_mov_b32_e32 v28, v132
	v_mov_b32_e32 v29, v134
	v_mov_b32_e32 v26, v133
	v_mov_b32_e32 v27, v135
	v_mov_b32_e32 v30, v144
	v_mov_b32_e32 v31, v146
	v_mov_b32_e32 v58, v145
	v_mov_b32_e32 v59, v147
	v_mov_b32_e32 v34, v140
	v_mov_b32_e32 v35, v142
	v_mov_b32_e32 v32, v141
	v_mov_b32_e32 v33, v143
	v_mov_b32_e32 v36, v152
	v_mov_b32_e32 v37, v154
	v_mov_b32_e32 v60, v153
	v_mov_b32_e32 v61, v155
	v_mov_b32_e32 v40, v148
	v_mov_b32_e32 v41, v150
	v_mov_b32_e32 v38, v149
	v_mov_b32_e32 v39, v151
	v_mov_b32_e32 v42, v160
	v_mov_b32_e32 v43, v162
	v_mov_b32_e32 v62, v161
	v_mov_b32_e32 v63, v163
	v_mov_b32_e32 v46, v156
	v_mov_b32_e32 v47, v158
	v_mov_b32_e32 v44, v157
	v_mov_b32_e32 v45, v159
	s_branch .LBB0_1573
.LBB0_1588:
	v_readlane_b32 s2, v254, 2
	v_readlane_b32 s3, v254, 3
	s_barrier
	s_cmp_ge_u32 s77, 4
	s_cbranch_scc0 .Lmy_attn_noprio
	s_setprio 1
.Lmy_attn_noprio:
	s_load_dwordx4 s[20:23], s[2:3], 0xf0
	s_mov_b32 s2, s77
	v_mbcnt_lo_u32_b32 v0, -1, 0
	v_mbcnt_hi_u32_b32 v0, -1, v0
	s_mov_b32 s7, s87
	v_readlane_b32 s2, v254, 0
	s_mov_b32 s12, s2
	s_and_b32 s2, s12, 7
	s_cmp_eq_u32 s2, 0
	v_readlane_b32 s3, v254, 1
	s_cbranch_scc0 .LBB0_1590
	s_ashr_i32 s3, s7, 31
	s_lshr_b32 s3, s3, 29
	s_add_i32 s3, s7, s3
	s_ashr_i32 s13, s3, 3
	s_and_b32 s3, s3, -8
	s_ashr_i32 s2, s12, 3
	s_sub_i32 s3, s7, s3
	s_mul_i32 s2, s2, s3
	s_add_i32 s7, s2, s13

; __device__ __forceinline__ int ltid(int wv) { int l; asm volatile("v_mbcnt_lo_u32_b32 %0, -1, 0\n\tv_mbcnt_hi_u32_b32 %0, -1, %0" : "=v"(l)); asm volatile("" : "+s"(wv)); return (wv << 6) | l; }
; __device__ __forceinline__ unsigned xb_add(unsigned* p, unsigned v) { return __hip_atomic_fetch_add(p, v, __ATOMIC_RELAXED, __HIP_MEMORY_SCOPE_AGENT); }
; __device__ __forceinline__ void xcd_barrier(const XcdBarrier& b, int wv) {
;     asm volatile("s_waitcnt vmcnt(0)" ::: "memory");
;     __syncthreads();
;     if (ltid(wv) == 0) {
;         unsigned* bar = b.bar;
;         __builtin_amdgcn_s_waitcnt(0);
;         unsigned nloc = b.st[0], nx = b.st[1];
;         if (nloc == 0u) { xcd_barrier_complete(bar, b.x, nloc, nx); b.st[0] = nloc; b.st[1] = nx; }
;         const unsigned old = xb_add(&bar[XB_XSUB(b.x)], 1u);
.LBB0_1672:
	v_readlane_b32 s2, v254, 2
	v_readlane_b32 s3, v254, 3
	s_setprio 0
	s_getreg_b32 s7, hwreg(HW_REG_XCC_ID, 0, 4)
	s_waitcnt vmcnt(0)
	s_barrier
	v_mbcnt_lo_u32_b32 v0, -1, 0
	v_mbcnt_hi_u32_b32 v0, -1, v0
	s_mov_b32 s12, s77
	s_nop 0
	v_lshl_or_b32 v0, s12, 6, v0
	v_cmp_eq_u32_e32 vcc, 0, v0
	s_and_saveexec_b64 s[16:17], vcc
	s_cbranch_execz .LBB0_1724
	s_load_dwordx2 s[18:19], s[2:3], 0xf8
	v_readlane_b32 s2, v254, 41
	s_waitcnt vmcnt(0) expcnt(0) lgkmcnt(0)
	s_and_b32 s7, s7, 15
	v_mov_b32_e32 v0, s2
	ds_read_b32 v3, v0
	v_readlane_b32 s2, v254, 42
	s_waitcnt lgkmcnt(0)
	v_cmp_ne_u32_e32 vcc, 0, v3
	v_mov_b32_e32 v0, s2
	ds_read_b32 v2, v0
	s_cbranch_vccnz .LBB0_1688
	s_add_u32 s2, s18, 0x1200
	s_addc_u32 s3, s19, 0
	s_add_u32 s20, s18, 0x1400
	s_addc_u32 s21, s19, 0
	s_add_u32 s22, s18, 0x1500
	s_addc_u32 s23, s19, 0
	s_add_u32 s24, s18, 0x1600
	s_addc_u32 s25, s19, 0
	s_add_u32 s26, s18, 0x1700
	s_addc_u32 s27, s19, 0
	s_add_u32 s28, s18, 0x1800
	s_addc_u32 s29, s19, 0
	s_add_u32 s34, s18, 0x1900
	s_addc_u32 s35, s19, 0
	s_add_u32 s36, s18, 0x1a00
	s_addc_u32 s37, s19, 0
	s_add_u32 s38, s18, 0x1b00
	s_addc_u32 s39, s19, 0
	s_add_u32 s40, s18, 0x1c00
	s_addc_u32 s41, s19, 0
	s_add_u32 s42, s18, 0x1d00
	s_addc_u32 s43, s19, 0
	s_add_u32 s44, s18, 0x1e00
	s_addc_u32 s45, s19, 0
	s_add_u32 s46, s18, 0x1f00
	s_addc_u32 s47, s19, 0
	s_add_u32 s48, s18, 0x2000
	s_addc_u32 s49, s19, 0
	s_add_u32 s50, s18, 0x2100
	s_addc_u32 s51, s19, 0
	s_add_u32 s52, s18, 0x2200
	s_addc_u32 s53, s19, 0
	s_add_u32 s82, s18, 0x2300
	s_addc_u32 s83, s19, 0
	s_mov_b32 s12, 1
	s_branch .LBB0_1676
